# v5 + P1 fp8 transpose tail: four column-amax loads per tile issued together (v249-251, next_free_vgpr 252)
# baseline (speedup 1.0000x reference)
.LBB0_217:
	s_and_b32 s4, s9, 15
	s_lshl_b32 s0, s4, 6
	s_and_b32 s2, s18, 0xffffffc0
	v_or_b32_e32 v0, s0, v129
	s_ashr_i32 s3, s2, 31
	v_mul_u32_u24_e32 v0, 0x1e00, v0
	v_lshl_add_u64 v[8:9], s[2:3], 2, v[4:5]
	v_lshlrev_b32_e32 v0, 2, v0
	v_lshl_add_u64 v[10:11], v[8:9], 0, v[0:1]
	v_or_b32_e32 v0, s0, v141
	v_mul_u32_u24_e32 v0, 0x1e00, v0
	v_lshlrev_b32_e32 v0, 2, v0
	v_lshl_add_u64 v[12:13], v[8:9], 0, v[0:1]
	v_or_b32_e32 v0, s0, v178
	v_mul_u32_u24_e32 v0, 0x1e00, v0
	v_lshlrev_b32_e32 v0, 2, v0
	v_lshl_add_u64 v[20:21], v[8:9], 0, v[0:1]
	v_or_b32_e32 v0, s0, v179
	v_mul_u32_u24_e32 v0, 0x1e00, v0
	v_lshlrev_b32_e32 v0, 2, v0
	v_lshl_add_u64 v[22:23], v[8:9], 0, v[0:1]
	v_or_b32_e32 v0, s0, v180
	v_mul_u32_u24_e32 v0, 0x1e00, v0
	v_lshlrev_b32_e32 v0, 2, v0
	v_lshl_add_u64 v[24:25], v[8:9], 0, v[0:1]
	v_or_b32_e32 v0, s0, v181
	v_mul_u32_u24_e32 v0, 0x1e00, v0
	v_lshlrev_b32_e32 v0, 2, v0
	v_lshl_add_u64 v[26:27], v[8:9], 0, v[0:1]
	v_or_b32_e32 v0, s0, v182
	v_mul_u32_u24_e32 v0, 0x1e00, v0
	v_lshlrev_b32_e32 v0, 2, v0
	v_lshl_add_u64 v[28:29], v[8:9], 0, v[0:1]
	v_or_b32_e32 v0, s0, v183
	v_mul_u32_u24_e32 v0, 0x1e00, v0
	v_lshlrev_b32_e32 v0, 2, v0
	v_lshl_add_u64 v[30:31], v[8:9], 0, v[0:1]
	v_or_b32_e32 v0, s0, v184
	v_mul_u32_u24_e32 v0, 0x1e00, v0
	v_lshlrev_b32_e32 v0, 2, v0
	s_barrier
	global_load_dword v3, v[10:11], off
	global_load_dword v19, v[12:13], off
	global_load_dword v32, v[20:21], off
	global_load_dword v33, v[22:23], off
	global_load_dword v34, v[24:25], off
	global_load_dword v35, v[26:27], off
	global_load_dword v36, v[28:29], off
	s_nop 0
	global_load_dword v30, v[30:31], off
	v_lshl_add_u64 v[10:11], v[8:9], 0, v[0:1]
	v_or_b32_e32 v0, s0, v185
	v_mul_u32_u24_e32 v0, 0x1e00, v0
	v_lshlrev_b32_e32 v0, 2, v0
	v_lshl_add_u64 v[12:13], v[8:9], 0, v[0:1]
	v_or_b32_e32 v0, s0, v186
	v_mul_u32_u24_e32 v0, 0x1e00, v0
	v_lshlrev_b32_e32 v0, 2, v0
	v_lshl_add_u64 v[20:21], v[8:9], 0, v[0:1]
	v_or_b32_e32 v0, s0, v187
	v_mul_u32_u24_e32 v0, 0x1e00, v0
	v_lshlrev_b32_e32 v0, 2, v0
	v_lshl_add_u64 v[22:23], v[8:9], 0, v[0:1]
	v_or_b32_e32 v0, s0, v188
	v_mul_u32_u24_e32 v0, 0x1e00, v0
	v_lshlrev_b32_e32 v0, 2, v0
	v_lshl_add_u64 v[24:25], v[8:9], 0, v[0:1]
	v_add_u32_e32 v0, s0, v189
	v_mul_u32_u24_e32 v0, 0x1e00, v0
	v_lshlrev_b32_e32 v0, 2, v0
	v_lshl_add_u64 v[26:27], v[8:9], 0, v[0:1]
	v_add_u32_e32 v0, s0, v190
	v_mul_u32_u24_e32 v0, 0x1e00, v0
	v_lshlrev_b32_e32 v0, 2, v0
	v_lshl_add_u64 v[28:29], v[8:9], 0, v[0:1]
	v_add_u32_e32 v0, s0, v191
	v_mul_u32_u24_e32 v0, 0x1e00, v0
	v_lshlrev_b32_e32 v0, 2, v0
	v_lshl_add_u64 v[8:9], v[8:9], 0, v[0:1]
	global_load_dword v0, v[10:11], off
	s_nop 0
	global_load_dword v10, v[12:13], off
	global_load_dword v11, v[20:21], off
	s_nop 0
	global_load_dword v12, v[22:23], off
	global_load_dword v13, v[24:25], off
	global_load_dword v20, v[26:27], off
	global_load_dword v21, v[28:29], off
	s_nop 0
	global_load_dword v8, v[8:9], off
	s_waitcnt vmcnt(15)
	ds_write_b32 v14, v3
	s_waitcnt vmcnt(14)
	ds_write_b32 v14, v19 offset:1040
	s_waitcnt vmcnt(13)
	ds_write_b32 v14, v32 offset:2080
	s_waitcnt vmcnt(12)
	ds_write_b32 v14, v33 offset:3120
	s_waitcnt vmcnt(11)
	ds_write_b32 v14, v34 offset:4160
	s_waitcnt vmcnt(10)
	ds_write_b32 v14, v35 offset:5200
	s_waitcnt vmcnt(9)
	ds_write_b32 v14, v36 offset:6240
	s_waitcnt vmcnt(8)
	ds_write_b32 v14, v30 offset:7280
	s_waitcnt vmcnt(7)
	ds_write_b32 v14, v0 offset:8320
	s_waitcnt vmcnt(6)
	ds_write_b32 v14, v10 offset:9360
	s_waitcnt vmcnt(5)
	ds_write_b32 v14, v11 offset:10400
	s_waitcnt vmcnt(4)
	ds_write_b32 v14, v12 offset:11440
	s_waitcnt vmcnt(3)
	ds_write_b32 v14, v13 offset:12480
	s_waitcnt vmcnt(2)
	ds_write_b32 v14, v20 offset:13520
	s_waitcnt vmcnt(1)
	ds_write_b32 v14, v21 offset:14560
	s_waitcnt vmcnt(0)
	ds_write_b32 v14, v8 offset:15600
	v_or_b32_e32 v10, s2, v136
	v_ashrrev_i32_e32 v11, 31, v10
	v_lshl_add_u64 v[8:9], v[10:11], 2, s[58:59]
	s_waitcnt lgkmcnt(0)
	s_barrier
	global_load_dword v0, v[8:9], off
	global_load_dword v249, v[8:9], off offset:64
	global_load_dword v250, v[8:9], off offset:128
	global_load_dword v251, v[8:9], off offset:192
	ds_read2_b32 v[12:13], v15 offset1:65
	ds_read2_b32 v[20:21], v15 offset0:130 offset1:195
	v_lshl_add_u64 v[8:9], v[6:7], 0, s[0:1]
	s_waitcnt vmcnt(0)
	v_div_scale_f32 v3, s[6:7], v0, v0, s8
	v_rcp_f32_e32 v19, v3
	v_div_scale_f32 v22, vcc, s8, v0, s8
	v_fma_f32 v23, -v3, v19, 1.0
	v_fmac_f32_e32 v19, v23, v19
	v_mul_f32_e32 v23, v22, v19
	v_fma_f32 v24, -v3, v23, v22
	v_fmac_f32_e32 v23, v24, v19
	v_fma_f32 v3, -v3, v23, v22
	v_div_fmas_f32 v3, v3, v19, v23
	v_div_fixup_f32 v3, v3, v0, s8
	v_cmp_lt_f32_e32 vcc, 0, v0
	v_mov_b32_e32 v19, v1
	s_nop 0
	v_cndmask_b32_e32 v3, 1.0, v3, vcc
	s_waitcnt lgkmcnt(1)
	v_mul_f32_e32 v12, v12, v3
	v_mul_f32_e32 v13, v13, v3
	v_cvt_pk_fp8_f32 v19, v12, v13
	s_waitcnt lgkmcnt(0)
	v_mul_f32_e32 v13, v3, v20
	v_mul_f32_e32 v3, v3, v21
	v_or_b32_e32 v12, s4, v2
	v_cvt_pk_fp8_f32 v19, v13, v3 op_sel:[0,0,1]
	v_cmp_eq_u32_e64 s[6:7], 0, v12
	v_lshlrev_b64 v[12:13], 10, v[10:11]
	v_lshl_add_u64 v[12:13], v[8:9], 0, v[12:13]
	global_store_dword v[12:13], v19, off
	s_and_saveexec_b64 s[4:5], s[6:7]
	s_cbranch_execz .LBB0_219
	v_mul_f32_e32 v0, 0x3b924925, v0
	v_cndmask_b32_e32 v0, 1.0, v0, vcc
	v_lshl_add_u64 v[10:11], v[10:11], 2, s[56:57]
	global_store_dword v[10:11], v0, off
.LBB0_219:
	s_or_b64 exec, exec, s[4:5]
	v_lshl_add_u64 v[10:11], s[2:3], 0, v[136:137]
	v_lshl_add_u64 v[12:13], v[10:11], 2, s[58:59]
	v_mov_b32_e32 v0, v249
	ds_read2_b32 v[20:21], v15 offset0:16 offset1:81
	ds_read2_b32 v[22:23], v15 offset0:146 offset1:211
	v_mov_b32_e32 v3, v1
	v_lshl_add_u64 v[10:11], v[10:11], 2, s[56:57]
	v_div_scale_f32 v19, s[4:5], v0, v0, s8
	v_rcp_f32_e32 v24, v19
	v_div_scale_f32 v25, vcc, s8, v0, s8
	v_fma_f32 v26, -v19, v24, 1.0
	v_fmac_f32_e32 v24, v26, v24
	v_mul_f32_e32 v26, v25, v24
	v_fma_f32 v27, -v19, v26, v25
	v_fmac_f32_e32 v26, v27, v24
	v_fma_f32 v19, -v19, v26, v25
	v_div_fmas_f32 v19, v19, v24, v26
	v_div_fixup_f32 v19, v19, v0, s8
	v_cmp_lt_f32_e32 vcc, 0, v0
	s_nop 1
	v_cndmask_b32_e32 v19, 1.0, v19, vcc
	s_waitcnt lgkmcnt(1)
	v_mul_f32_e32 v20, v20, v19
	v_mul_f32_e32 v21, v21, v19
	v_cvt_pk_fp8_f32 v3, v20, v21
	s_waitcnt lgkmcnt(0)
	v_mul_f32_e32 v21, v19, v22
	v_mul_f32_e32 v19, v19, v23
	v_add_u32_e32 v20, s2, v16
	v_cvt_pk_fp8_f32 v3, v21, v19 op_sel:[0,0,1]
	v_ashrrev_i32_e32 v21, 31, v20
	v_lshlrev_b64 v[20:21], 10, v[20:21]
	v_lshl_add_u64 v[20:21], v[8:9], 0, v[20:21]
	global_store_dword v[20:21], v3, off
	s_and_saveexec_b64 s[4:5], s[6:7]
	s_cbranch_execz .LBB0_221
	v_mul_f32_e32 v0, 0x3b924925, v0
	v_cndmask_b32_e32 v0, 1.0, v0, vcc
	global_store_dword v[10:11], v0, off offset:64
.LBB0_221:
	s_or_b64 exec, exec, s[4:5]
	v_mov_b32_e32 v0, v250
	ds_read2_b32 v[20:21], v15 offset0:32 offset1:97
	ds_read2_b32 v[22:23], v15 offset0:162 offset1:227
	v_div_scale_f32 v3, s[4:5], v0, v0, s8
	v_rcp_f32_e32 v19, v3
	v_div_scale_f32 v24, vcc, s8, v0, s8
	v_fma_f32 v25, -v3, v19, 1.0
	v_fmac_f32_e32 v19, v25, v19
	v_mul_f32_e32 v25, v24, v19
	v_fma_f32 v26, -v3, v25, v24
	v_fmac_f32_e32 v25, v26, v19
	v_fma_f32 v3, -v3, v25, v24
	v_div_fmas_f32 v3, v3, v19, v25
	v_div_fixup_f32 v3, v3, v0, s8
	v_cmp_lt_f32_e32 vcc, 0, v0
	v_mov_b32_e32 v24, v1
	s_nop 0
	v_cndmask_b32_e32 v3, 1.0, v3, vcc
	s_waitcnt lgkmcnt(1)
	v_mul_f32_e32 v19, v20, v3
	v_mul_f32_e32 v20, v21, v3
	v_cvt_pk_fp8_f32 v24, v19, v20
	s_waitcnt lgkmcnt(0)
	v_mul_f32_e32 v19, v3, v22
	v_mul_f32_e32 v3, v3, v23
	v_add_u32_e32 v20, s2, v17
	v_cvt_pk_fp8_f32 v24, v19, v3 op_sel:[0,0,1]
	v_ashrrev_i32_e32 v21, 31, v20
	v_lshlrev_b64 v[20:21], 10, v[20:21]
	v_lshl_add_u64 v[20:21], v[8:9], 0, v[20:21]
	global_store_dword v[20:21], v24, off
	s_and_saveexec_b64 s[4:5], s[6:7]
	s_cbranch_execz .LBB0_223
	v_mul_f32_e32 v0, 0x3b924925, v0
	v_cndmask_b32_e32 v0, 1.0, v0, vcc
	global_store_dword v[10:11], v0, off offset:128
.LBB0_223:
	s_or_b64 exec, exec, s[4:5]
	v_mov_b32_e32 v0, v251
	ds_read2_b32 v[12:13], v15 offset0:48 offset1:113
	ds_read2_b32 v[20:21], v15 offset0:178 offset1:243
	v_div_scale_f32 v3, s[4:5], v0, v0, s8
	v_rcp_f32_e32 v19, v3
	v_div_scale_f32 v22, vcc, s8, v0, s8
	v_fma_f32 v23, -v3, v19, 1.0
	v_fmac_f32_e32 v19, v23, v19
	v_mul_f32_e32 v23, v22, v19
	v_fma_f32 v24, -v3, v23, v22
	v_fmac_f32_e32 v23, v24, v19
	v_fma_f32 v3, -v3, v23, v22
	v_div_fmas_f32 v3, v3, v19, v23
	v_div_fixup_f32 v3, v3, v0, s8
	v_cmp_lt_f32_e32 vcc, 0, v0
	v_mov_b32_e32 v19, v1
	s_nop 0
	v_cndmask_b32_e32 v3, 1.0, v3, vcc
	s_waitcnt lgkmcnt(1)
	v_mul_f32_e32 v12, v12, v3
	v_mul_f32_e32 v13, v13, v3
	v_cvt_pk_fp8_f32 v19, v12, v13
	s_waitcnt lgkmcnt(0)
	v_mul_f32_e32 v13, v3, v20
	v_mul_f32_e32 v3, v3, v21
	v_add_u32_e32 v12, s2, v18
	v_cvt_pk_fp8_f32 v19, v13, v3 op_sel:[0,0,1]
	v_ashrrev_i32_e32 v13, 31, v12
	v_lshlrev_b64 v[12:13], 10, v[12:13]
	v_lshl_add_u64 v[8:9], v[8:9], 0, v[12:13]
	global_store_dword v[8:9], v19, off
	s_and_saveexec_b64 s[2:3], s[6:7]
	s_cbranch_execz .LBB0_216
	v_mul_f32_e32 v0, 0x3b924925, v0
	v_cndmask_b32_e32 v0, 1.0, v0, vcc
	global_store_dword v[10:11], v0, off offset:192
	s_branch .LBB0_216

	.amdhsa_kernel _Z11mega_kernel6Params
		.amdhsa_group_segment_fixed_size 79892
		.amdhsa_private_segment_fixed_size 0
		.amdhsa_kernarg_size 696
		.amdhsa_user_sgpr_count 2
		.amdhsa_user_sgpr_dispatch_ptr 0
		.amdhsa_user_sgpr_queue_ptr 0
		.amdhsa_user_sgpr_kernarg_segment_ptr 1
		.amdhsa_user_sgpr_dispatch_id 0
		.amdhsa_user_sgpr_kernarg_preload_length 0
		.amdhsa_user_sgpr_kernarg_preload_offset 0
		.amdhsa_user_sgpr_private_segment_size 0
		.amdhsa_uses_dynamic_stack 0
		.amdhsa_enable_private_segment 0
		.amdhsa_system_sgpr_workgroup_id_x 1
		.amdhsa_system_sgpr_workgroup_id_y 0
		.amdhsa_system_sgpr_workgroup_id_z 0
		.amdhsa_system_sgpr_workgroup_info 0
		.amdhsa_system_vgpr_workitem_id 2
		.amdhsa_next_free_vgpr 252
		.amdhsa_next_free_sgpr 98
		.amdhsa_accum_offset 252
		.amdhsa_reserve_vcc 1
		.amdhsa_float_round_mode_32 0
		.amdhsa_float_round_mode_16_64 0
		.amdhsa_float_denorm_mode_32 3
		.amdhsa_float_denorm_mode_16_64 3
		.amdhsa_dx10_clamp 1
		.amdhsa_ieee_mode 1
		.amdhsa_fp16_overflow 0
		.amdhsa_tg_split 0
		.amdhsa_exception_fp_ieee_invalid_op 0
		.amdhsa_exception_fp_denorm_src 0
		.amdhsa_exception_fp_ieee_div_zero 0
		.amdhsa_exception_fp_ieee_overflow 0
		.amdhsa_exception_fp_ieee_underflow 0
		.amdhsa_exception_fp_ieee_inexact 0
		.amdhsa_exception_int_div_zero 0
	.end_amdhsa_kernel

amdhsa.kernels:
  - .agpr_count:     0
    .args:
      - .offset:         0
        .size:           440
        .value_kind:     by_value
      - .offset:         440
        .size:           4
        .value_kind:     hidden_block_count_x
      - .offset:         444
        .size:           4
        .value_kind:     hidden_block_count_y
      - .offset:         448
        .size:           4
        .value_kind:     hidden_block_count_z
      - .offset:         452
        .size:           2
        .value_kind:     hidden_group_size_x
      - .offset:         454
        .size:           2
        .value_kind:     hidden_group_size_y
      - .offset:         456
        .size:           2
        .value_kind:     hidden_group_size_z
      - .offset:         458
        .size:           2
        .value_kind:     hidden_remainder_x
      - .offset:         460
        .size:           2
        .value_kind:     hidden_remainder_y
      - .offset:         462
        .size:           2
        .value_kind:     hidden_remainder_z
      - .offset:         480
        .size:           8
        .value_kind:     hidden_global_offset_x
      - .offset:         488
        .size:           8
        .value_kind:     hidden_global_offset_y
      - .offset:         496
        .size:           8
        .value_kind:     hidden_global_offset_z
      - .offset:         504
        .size:           2
        .value_kind:     hidden_grid_dims
      - .offset:         528
        .size:           8
        .value_kind:     hidden_multigrid_sync_arg
    .group_segment_fixed_size: 79892
    .kernarg_segment_align: 8
    .kernarg_segment_size: 696
    .language:       OpenCL C
    .language_version:
      - 2
      - 0
    .max_flat_workgroup_size: 256
    .name:           _Z11mega_kernel6Params
    .private_segment_fixed_size: 0
    .sgpr_count:     104
    .sgpr_spill_count: 225
    .symbol:         _Z11mega_kernel6Params.kd
    .uniform_work_group_size: 1
    .uses_dynamic_stack: false
    .vgpr_count:     252
    .vgpr_spill_count: 0
    .wavefront_size: 64
